# v46: grid barrier top level polls the top counter directly (leader add without return, no generation word hop)
# speedup vs baseline: 1.0452x; 1.0020x over previous
.LBB0_1161:
	s_or_b64 exec, exec, s[8:9]
	v_cvt_f32_u32_e32 v5, v3
	s_waitcnt vmcnt(0)
	v_readfirstlane_b32 s6, v4
	v_sub_u32_e32 v4, 0, v3
	v_rcp_iflag_f32_e32 v5, v5
	v_add_u32_e32 v6, s6, v0
	v_mul_f32_e32 v5, 0x4f7ffffe, v5
	v_cvt_u32_f32_e32 v5, v5
	v_mul_lo_u32 v0, v4, v5
	v_mul_hi_u32 v0, v5, v0
	v_add_u32_e32 v0, v5, v0
	v_mul_hi_u32 v0, v6, v0
	v_mul_lo_u32 v4, v0, v3
	v_sub_u32_e32 v4, v6, v4
	v_add_u32_e32 v5, 1, v0
	v_cmp_ge_u32_e32 vcc, v4, v3
	s_nop 1
	v_cndmask_b32_e32 v0, v0, v5, vcc
	v_sub_u32_e32 v5, v4, v3
	v_cndmask_b32_e32 v4, v4, v5, vcc
	v_add_u32_e32 v5, 1, v0
	v_cmp_ge_u32_e32 vcc, v4, v3
	v_add_u32_e32 v4, 1, v6
	s_nop 0
	v_cndmask_b32_e32 v0, v0, v5, vcc
	v_mul_lo_u32 v5, v3, v0
	v_add_u32_e32 v3, v5, v3
	v_cmp_ne_u32_e32 vcc, v4, v3
	s_and_b64 s[6:7], vcc, exec
	v_add_u32_e32 v5, 1, v0
	v_mul_lo_u32 v5, v5, v2
	v_readlane_b32 s10, v254, 17
	v_readlane_b32 s11, v254, 18
	s_cbranch_scc1 .Lxb_poll
	buffer_wbl2 sc1
	s_waitcnt vmcnt(0) lgkmcnt(0)
	global_atomic_add v1, v226, s[10:11]
.Lxb_poll:
	s_mov_b32 s8, 0
	s_nop 3
.Lxb_spin:
	global_load_dword v6, v1, s[10:11] sc1
	s_waitcnt vmcnt(0)
	v_cmp_ge_u32_e32 vcc, v6, v5
	s_cbranch_vccnz .Lxb_done
	s_add_i32 s8, s8, 1
	s_cmp_gt_u32 s8, 0x100000
	s_cbranch_scc1 .Lxb_done
	s_sleep 1
	s_branch .Lxb_spin
.Lxb_done:
	buffer_inv sc1
	s_waitcnt vmcnt(0)
	s_getpc_b64 s[98:99]
